# F12 + latent attention step barrier waits only for the LDS-DMA (vmcnt), not for the 4 V-fragment prefetch reads issued just before it
# speedup vs baseline: 1.0062x; 1.0014x over previous
.LBB1_530:
	v_add3_u32 v64, s25, v243, v224
	ds_read_b128 v[190:193], v64 offset:16384
	ds_read_b128 v[186:189], v64 offset:20480
	ds_read_b128 v[182:185], v64 offset:24576
	ds_read_b128 v[142:145], v64 offset:28672
	s_waitcnt vmcnt(0)
	s_barrier
	s_add_u32 s26, s26, 0x80
	s_addc_u32 s27, s27, 0
	v_add_f32_e32 v238, v66, v238
	s_cmpk_eq_i32 s26, 0x2100
	v_lshl_add_u64 v[212:213], v[212:213], 0, s[34:35]
	s_cbranch_scc1 .Lat_exit
	s_mov_b32 s30, s11
	s_mov_b32 s11, s10
	s_mov_b32 s10, s24
	s_branch .LBB1_522
